# quarter units of the residual GEMM: hand-written K loop, one K-tile per ping-pong phase, 4-deep LDS ring over the unused half regions, LDS-DMA 3 K-tiles ahead
# speedup vs baseline: 1.1120x; 1.0038x over previous
; #define PG8_STAGE(bufoff, gbase, voff) do { _Pragma("unroll") for (int _i = 0; _i < 2; ++_i) \
;         __builtin_amdgcn_global_load_lds((const unsigned*)((const char*)(gbase) + (voff)[_i]), (PG8_LAS unsigned*)(lds + (bufoff) + ldsw + _i * 8192), 16, 0, 0); } while (0)
; #define PG8_LDA(dst, b, h) do { _Pragma("unroll") for (int m = 0; m < 4; ++m) _Pragma("unroll") for (int k = 0; k < 2; ++k) dst[m][k] = *(const PG8_LAS bf16x8*)(lds + PG8_SA(b, h) + aoff + m * 2048 + k * 1024); } while (0)
; #define PG8_LDB(dst, b, h) do { _Pragma("unroll") for (int n = 0; n < 2; ++n) _Pragma("unroll") for (int k = 0; k < 2; ++k) dst[n][k] = *(const PG8_LAS bf16x8*)(lds + PG8_SB(b, h) + boff + n * 2048 + k * 1024); } while (0)
; template <class Epi, class Sched, bool ALIGN_EPI = false, bool SP2 = false>
; __device__ __forceinline__ void gemm_phase(PG8_LAS unsigned char* lds, const Gemm g, const Sched& S, const Epi& E) {
;     ...
;         for (int t = 0; t < nt; t += 2) {
;             const bool last = (t == nt - 2);
;             const char* a1 = cA + (size_t)(t + 1) * kstep;
;             const char* a2 = last ? nA : cA + (size_t)(t + 2) * kstep; const char* b2 = last ? nB : cB + (size_t)(t + 2) * kstep;
;             const char* a3 = a2 + kstep; const char* b3 = b2 + kstep;
;             if (last && has_next) S.a_ready(nxt);
;             if constexpr (SP2) {
;             PG8_LDB(B0, 0, 0); PG8_LDB(B1, 0, 1); PG8_SCHED; PG8_LDA(At, 0, 0); PG8_STAGE(PG8_SA(1, 1), a1 + hstep, voffA);
;             PG8_WAIT_V(8); PG8_WAIT_L(0); PG8_BAR; PG8_MMA(0, 0, At, B0); PG8_MMA(0, 1, At, B1); PG8_BAR; PG8_SCHED;
;             PG8_LDA(At, 0, 1); PG8_STAGE(PG8_SB(0, 0), b2, voffB); PG8_STAGE(PG8_SB(0, 1), b2 + hstep, voffB); PG8_STAGE(PG8_SA(0, 0), a2, voffA);
;             PG8_WAIT_V(8); PG8_WAIT_L(0); PG8_BAR; PG8_MMA(1, 0, At, B0); PG8_MMA(1, 1, At, B1); PG8_BAR; PG8_SCHED;
;             PG8_LDB(B0, 1, 0); PG8_LDB(B1, 1, 1); PG8_SCHED; PG8_LDA(At, 1, 0); PG8_STAGE(PG8_SA(0, 1), a2 + hstep, voffA);
;             PG8_WAIT_V(8); PG8_WAIT_L(0); PG8_BAR; PG8_MMA(0, 0, At, B0); PG8_MMA(0, 1, At, B1); PG8_BAR; PG8_SCHED;
;             PG8_LDA(At, 1, 1); PG8_STAGE(PG8_SB(1, 0), b3, voffB); PG8_STAGE(PG8_SB(1, 1), b3 + hstep, voffB); PG8_STAGE(PG8_SA(1, 0), a3, voffA);
;             PG8_WAIT_V(8); PG8_WAIT_L(0); PG8_BAR; PG8_MMA(1, 0, At, B0); PG8_MMA(1, 1, At, B1); PG8_BAR; PG8_SCHED;
.Lkq_1:
	s_waitcnt vmcnt(0)
	s_barrier
	s_mov_b64 s[76:77], s[48:49]
	s_add_u32 vcc_lo, s80, 0xffffff80
	s_addc_u32 vcc_hi, s81, -1
	s_add_u32 s76, s76, 0x80
	s_addc_u32 s77, s77, 0
	s_add_u32 vcc_lo, vcc_lo, 0x80
	s_addc_u32 vcc_hi, vcc_hi, 0
	v_lshl_add_u64 v[136:137], s[76:77], 0, v[0:1]
	s_add_i32 m0, s94, 0x4000
	v_lshl_add_u64 v[144:145], s[76:77], 0, v[130:131]
	global_load_lds_dwordx4 v[136:137], off
	s_add_i32 m0, s94, 0x6000
	s_nop 0
	global_load_lds_dwordx4 v[144:145], off
	v_lshl_add_u64 v[182:183], vcc, 0, v[0:1]
	s_add_i32 m0, s93, 0x14000
	v_lshl_add_u64 v[236:237], vcc, 0, v[130:131]
	global_load_lds_dwordx4 v[182:183], off
	s_add_i32 m0, s93, 0x16000
	s_nop 0
	global_load_lds_dwordx4 v[236:237], off
	s_add_u32 s76, s76, 0x80
	s_addc_u32 s77, s77, 0
	s_add_u32 vcc_lo, vcc_lo, 0x80
	s_addc_u32 vcc_hi, vcc_hi, 0
	s_mov_b32 s82, 3
	s_add_i32 s59, s79, -1
.Lkq_1_loop:
	v_add_u32_e32 v136, 0x10000, v147
	ds_read_b128 v[148:151], v136
	ds_read_b128 v[152:155], v136 offset:1024
	ds_read_b128 v[156:159], v136 offset:2048
	ds_read_b128 v[160:163], v136 offset:3072
	ds_read_b128 v[202:205], v165
	ds_read_b128 v[208:211], v165 offset:1024
	ds_read_b128 v[212:215], v165 offset:2048
	ds_read_b128 v[216:219], v165 offset:3072
	ds_read_b128 v[220:223], v165 offset:4096
	ds_read_b128 v[224:227], v165 offset:5120
	ds_read_b128 v[228:231], v165 offset:6144
	ds_read_b128 v[232:235], v165 offset:7168
	v_lshl_add_u64 v[136:137], s[76:77], 0, v[0:1]
	s_add_i32 m0, s94, 0xc000
	v_lshl_add_u64 v[144:145], s[76:77], 0, v[130:131]
	global_load_lds_dwordx4 v[136:137], off
	s_add_i32 m0, s94, 0xe000
	s_nop 0
	global_load_lds_dwordx4 v[144:145], off
	v_lshl_add_u64 v[182:183], vcc, 0, v[0:1]
	s_add_i32 m0, s93, 0x1c000
	v_lshl_add_u64 v[236:237], vcc, 0, v[130:131]
	global_load_lds_dwordx4 v[182:183], off
	s_add_i32 m0, s93, 0x1e000
	s_nop 0
	global_load_lds_dwordx4 v[236:237], off
	s_cmp_lt_u32 s82, s59
	s_cselect_b32 s83, 0x80, 0
	s_add_u32 s76, s76, s83
	s_addc_u32 s77, s77, 0
	s_add_u32 vcc_lo, vcc_lo, s83
	s_addc_u32 vcc_hi, vcc_hi, 0
	s_add_i32 s82, s82, 1
	s_waitcnt vmcnt(8)
	s_waitcnt lgkmcnt(0)
	s_barrier
	s_setprio 1
	v_mfma_f32_16x16x32_bf16 v[126:129], v[148:151], v[202:205], v[126:129]
	v_mfma_f32_16x16x32_bf16 v[122:125], v[156:159], v[202:205], v[122:125]
	v_mfma_f32_16x16x32_bf16 v[110:113], v[148:151], v[212:215], v[110:113]
	v_mfma_f32_16x16x32_bf16 v[106:109], v[156:159], v[212:215], v[106:109]
	v_mfma_f32_16x16x32_bf16 v[94:97], v[148:151], v[220:223], v[94:97]
	v_mfma_f32_16x16x32_bf16 v[90:93], v[156:159], v[220:223], v[90:93]
	v_mfma_f32_16x16x32_bf16 v[78:81], v[148:151], v[228:231], v[78:81]
	v_mfma_f32_16x16x32_bf16 v[74:77], v[156:159], v[228:231], v[74:77]
	v_mfma_f32_16x16x32_bf16 v[126:129], v[152:155], v[208:211], v[126:129]
	v_mfma_f32_16x16x32_bf16 v[122:125], v[160:163], v[208:211], v[122:125]
	v_mfma_f32_16x16x32_bf16 v[110:113], v[152:155], v[216:219], v[110:113]
	v_mfma_f32_16x16x32_bf16 v[106:109], v[160:163], v[216:219], v[106:109]
	v_mfma_f32_16x16x32_bf16 v[94:97], v[152:155], v[224:227], v[94:97]
	v_mfma_f32_16x16x32_bf16 v[90:93], v[160:163], v[224:227], v[90:93]
	v_mfma_f32_16x16x32_bf16 v[78:81], v[152:155], v[232:235], v[78:81]
	v_mfma_f32_16x16x32_bf16 v[74:77], v[160:163], v[232:235], v[74:77]
	s_setprio 0
	s_barrier
	v_add_u32_e32 v136, 0x18000, v147
	ds_read_b128 v[148:151], v136
	ds_read_b128 v[152:155], v136 offset:1024
	ds_read_b128 v[156:159], v136 offset:2048
	ds_read_b128 v[160:163], v136 offset:3072
	ds_read_b128 v[202:205], v165 offset:32768
	ds_read_b128 v[208:211], v165 offset:33792
	ds_read_b128 v[212:215], v165 offset:34816
	ds_read_b128 v[216:219], v165 offset:35840
	ds_read_b128 v[220:223], v165 offset:36864
	ds_read_b128 v[224:227], v165 offset:37888
	ds_read_b128 v[228:231], v165 offset:38912
	ds_read_b128 v[232:235], v165 offset:39936
	v_lshl_add_u64 v[136:137], s[76:77], 0, v[0:1]
	s_add_i32 m0, s94, 0x0
	v_lshl_add_u64 v[144:145], s[76:77], 0, v[130:131]
	global_load_lds_dwordx4 v[136:137], off
	s_add_i32 m0, s94, 0x2000
	s_nop 0
	global_load_lds_dwordx4 v[144:145], off
	v_lshl_add_u64 v[182:183], vcc, 0, v[0:1]
	s_add_i32 m0, s93, 0x10000
	v_lshl_add_u64 v[236:237], vcc, 0, v[130:131]
	global_load_lds_dwordx4 v[182:183], off
	s_add_i32 m0, s93, 0x12000
	s_nop 0
	global_load_lds_dwordx4 v[236:237], off
	s_cmp_lt_u32 s82, s59
	s_cselect_b32 s83, 0x80, 0
	s_add_u32 s76, s76, s83
	s_addc_u32 s77, s77, 0
	s_add_u32 vcc_lo, vcc_lo, s83
	s_addc_u32 vcc_hi, vcc_hi, 0
	s_add_i32 s82, s82, 1
	s_waitcnt vmcnt(8)
	s_waitcnt lgkmcnt(0)
	s_barrier
	s_setprio 1
	v_mfma_f32_16x16x32_bf16 v[126:129], v[148:151], v[202:205], v[126:129]
	v_mfma_f32_16x16x32_bf16 v[122:125], v[156:159], v[202:205], v[122:125]
	v_mfma_f32_16x16x32_bf16 v[110:113], v[148:151], v[212:215], v[110:113]
	v_mfma_f32_16x16x32_bf16 v[106:109], v[156:159], v[212:215], v[106:109]
	v_mfma_f32_16x16x32_bf16 v[94:97], v[148:151], v[220:223], v[94:97]
	v_mfma_f32_16x16x32_bf16 v[90:93], v[156:159], v[220:223], v[90:93]
	v_mfma_f32_16x16x32_bf16 v[78:81], v[148:151], v[228:231], v[78:81]
	v_mfma_f32_16x16x32_bf16 v[74:77], v[156:159], v[228:231], v[74:77]
	v_mfma_f32_16x16x32_bf16 v[126:129], v[152:155], v[208:211], v[126:129]
	v_mfma_f32_16x16x32_bf16 v[122:125], v[160:163], v[208:211], v[122:125]
	v_mfma_f32_16x16x32_bf16 v[110:113], v[152:155], v[216:219], v[110:113]
	v_mfma_f32_16x16x32_bf16 v[106:109], v[160:163], v[216:219], v[106:109]
	v_mfma_f32_16x16x32_bf16 v[94:97], v[152:155], v[224:227], v[94:97]
	v_mfma_f32_16x16x32_bf16 v[90:93], v[160:163], v[224:227], v[90:93]
	v_mfma_f32_16x16x32_bf16 v[78:81], v[152:155], v[232:235], v[78:81]
	v_mfma_f32_16x16x32_bf16 v[74:77], v[160:163], v[232:235], v[74:77]
	s_setprio 0
	s_barrier
; #define PG8_STAGE(bufoff, gbase, voff) do { _Pragma("unroll") for (int _i = 0; _i < 2; ++_i) \
;         __builtin_amdgcn_global_load_lds((const unsigned*)((const char*)(gbase) + (voff)[_i]), (PG8_LAS unsigned*)(lds + (bufoff) + ldsw + _i * 8192), 16, 0, 0); } while (0)
; #define PG8_LDA(dst, b, h) do { _Pragma("unroll") for (int m = 0; m < 4; ++m) _Pragma("unroll") for (int k = 0; k < 2; ++k) dst[m][k] = *(const PG8_LAS bf16x8*)(lds + PG8_SA(b, h) + aoff + m * 2048 + k * 1024); } while (0)
; #define PG8_LDB(dst, b, h) do { _Pragma("unroll") for (int n = 0; n < 2; ++n) _Pragma("unroll") for (int k = 0; k < 2; ++k) dst[n][k] = *(const PG8_LAS bf16x8*)(lds + PG8_SB(b, h) + boff + n * 2048 + k * 1024); } while (0)
; template <class Epi, class Sched, bool ALIGN_EPI = false, bool SP2 = false>
; __device__ __forceinline__ void gemm_phase(PG8_LAS unsigned char* lds, const Gemm g, const Sched& S, const Epi& E) {
;     ...
;         for (int t = 0; t < nt; t += 2) {
;             const bool last = (t == nt - 2);
;             const char* a1 = cA + (size_t)(t + 1) * kstep;
;             const char* a2 = last ? nA : cA + (size_t)(t + 2) * kstep; const char* b2 = last ? nB : cB + (size_t)(t + 2) * kstep;
;             const char* a3 = a2 + kstep; const char* b3 = b2 + kstep;
;             if (last && has_next) S.a_ready(nxt);
;             if constexpr (SP2) {
;             PG8_LDB(B0, 0, 0); PG8_LDB(B1, 0, 1); PG8_SCHED; PG8_LDA(At, 0, 0); PG8_STAGE(PG8_SA(1, 1), a1 + hstep, voffA);
;             PG8_WAIT_V(8); PG8_WAIT_L(0); PG8_BAR; PG8_MMA(0, 0, At, B0); PG8_MMA(0, 1, At, B1); PG8_BAR; PG8_SCHED;
;             PG8_LDA(At, 0, 1); PG8_STAGE(PG8_SB(0, 0), b2, voffB); PG8_STAGE(PG8_SB(0, 1), b2 + hstep, voffB); PG8_STAGE(PG8_SA(0, 0), a2, voffA);
;             PG8_WAIT_V(8); PG8_WAIT_L(0); PG8_BAR; PG8_MMA(1, 0, At, B0); PG8_MMA(1, 1, At, B1); PG8_BAR; PG8_SCHED;
;             PG8_LDB(B0, 1, 0); PG8_LDB(B1, 1, 1); PG8_SCHED; PG8_LDA(At, 1, 0); PG8_STAGE(PG8_SA(0, 1), a2 + hstep, voffA);
;             PG8_WAIT_V(8); PG8_WAIT_L(0); PG8_BAR; PG8_MMA(0, 0, At, B0); PG8_MMA(0, 1, At, B1); PG8_BAR; PG8_SCHED;
;             PG8_LDA(At, 1, 1); PG8_STAGE(PG8_SB(1, 0), b3, voffB); PG8_STAGE(PG8_SB(1, 1), b3 + hstep, voffB); PG8_STAGE(PG8_SA(1, 0), a3, voffA);
;             PG8_WAIT_V(8); PG8_WAIT_L(0); PG8_BAR; PG8_MMA(1, 0, At, B0); PG8_MMA(1, 1, At, B1); PG8_BAR; PG8_SCHED;
	v_add_u32_e32 v136, 0x14000, v147
	ds_read_b128 v[148:151], v136
	ds_read_b128 v[152:155], v136 offset:1024
	ds_read_b128 v[156:159], v136 offset:2048
	ds_read_b128 v[160:163], v136 offset:3072
	ds_read_b128 v[202:205], v165 offset:16384
	ds_read_b128 v[208:211], v165 offset:17408
	ds_read_b128 v[212:215], v165 offset:18432
	ds_read_b128 v[216:219], v165 offset:19456
	ds_read_b128 v[220:223], v165 offset:20480
	ds_read_b128 v[224:227], v165 offset:21504
	ds_read_b128 v[228:231], v165 offset:22528
	ds_read_b128 v[232:235], v165 offset:23552
	v_lshl_add_u64 v[136:137], s[76:77], 0, v[0:1]
	s_add_i32 m0, s94, 0x8000
	v_lshl_add_u64 v[144:145], s[76:77], 0, v[130:131]
	global_load_lds_dwordx4 v[136:137], off
	s_add_i32 m0, s94, 0xa000
	s_nop 0
	global_load_lds_dwordx4 v[144:145], off
	v_lshl_add_u64 v[182:183], vcc, 0, v[0:1]
	s_add_i32 m0, s93, 0x18000
	v_lshl_add_u64 v[236:237], vcc, 0, v[130:131]
	global_load_lds_dwordx4 v[182:183], off
	s_add_i32 m0, s93, 0x1a000
	s_nop 0
	global_load_lds_dwordx4 v[236:237], off
	s_cmp_lt_u32 s82, s59
	s_cselect_b32 s83, 0x80, 0
	s_add_u32 s76, s76, s83
	s_addc_u32 s77, s77, 0
	s_add_u32 vcc_lo, vcc_lo, s83
	s_addc_u32 vcc_hi, vcc_hi, 0
	s_add_i32 s82, s82, 1
	s_waitcnt vmcnt(8)
	s_waitcnt lgkmcnt(0)
	s_barrier
	s_setprio 1
	v_mfma_f32_16x16x32_bf16 v[126:129], v[148:151], v[202:205], v[126:129]
	v_mfma_f32_16x16x32_bf16 v[122:125], v[156:159], v[202:205], v[122:125]
	v_mfma_f32_16x16x32_bf16 v[110:113], v[148:151], v[212:215], v[110:113]
	v_mfma_f32_16x16x32_bf16 v[106:109], v[156:159], v[212:215], v[106:109]
	v_mfma_f32_16x16x32_bf16 v[94:97], v[148:151], v[220:223], v[94:97]
	v_mfma_f32_16x16x32_bf16 v[90:93], v[156:159], v[220:223], v[90:93]
	v_mfma_f32_16x16x32_bf16 v[78:81], v[148:151], v[228:231], v[78:81]
	v_mfma_f32_16x16x32_bf16 v[74:77], v[156:159], v[228:231], v[74:77]
	v_mfma_f32_16x16x32_bf16 v[126:129], v[152:155], v[208:211], v[126:129]
	v_mfma_f32_16x16x32_bf16 v[122:125], v[160:163], v[208:211], v[122:125]
	v_mfma_f32_16x16x32_bf16 v[110:113], v[152:155], v[216:219], v[110:113]
	v_mfma_f32_16x16x32_bf16 v[106:109], v[160:163], v[216:219], v[106:109]
	v_mfma_f32_16x16x32_bf16 v[94:97], v[152:155], v[224:227], v[94:97]
	v_mfma_f32_16x16x32_bf16 v[90:93], v[160:163], v[224:227], v[90:93]
	v_mfma_f32_16x16x32_bf16 v[78:81], v[152:155], v[232:235], v[78:81]
	v_mfma_f32_16x16x32_bf16 v[74:77], v[160:163], v[232:235], v[74:77]
	s_setprio 0
	s_barrier
	v_add_u32_e32 v136, 0x1c000, v147
	ds_read_b128 v[148:151], v136
	ds_read_b128 v[152:155], v136 offset:1024
	ds_read_b128 v[156:159], v136 offset:2048
	ds_read_b128 v[160:163], v136 offset:3072
	ds_read_b128 v[202:205], v165 offset:49152
	ds_read_b128 v[208:211], v165 offset:50176
	ds_read_b128 v[212:215], v165 offset:51200
	ds_read_b128 v[216:219], v165 offset:52224
	ds_read_b128 v[220:223], v165 offset:53248
	ds_read_b128 v[224:227], v165 offset:54272
	ds_read_b128 v[228:231], v165 offset:55296
	ds_read_b128 v[232:235], v165 offset:56320
	v_lshl_add_u64 v[136:137], s[76:77], 0, v[0:1]
	s_add_i32 m0, s94, 0x4000
	v_lshl_add_u64 v[144:145], s[76:77], 0, v[130:131]
	global_load_lds_dwordx4 v[136:137], off
	s_add_i32 m0, s94, 0x6000
	s_nop 0
	global_load_lds_dwordx4 v[144:145], off
	v_lshl_add_u64 v[182:183], vcc, 0, v[0:1]
	s_add_i32 m0, s93, 0x14000
	v_lshl_add_u64 v[236:237], vcc, 0, v[130:131]
	global_load_lds_dwordx4 v[182:183], off
	s_add_i32 m0, s93, 0x16000
	s_nop 0
	global_load_lds_dwordx4 v[236:237], off
	s_cmp_lt_u32 s82, s59
	s_cselect_b32 s83, 0x80, 0
	s_add_u32 s76, s76, s83
	s_addc_u32 s77, s77, 0
	s_add_u32 vcc_lo, vcc_lo, s83
	s_addc_u32 vcc_hi, vcc_hi, 0
	s_add_i32 s82, s82, 1
	s_waitcnt vmcnt(8)
	s_waitcnt lgkmcnt(0)
	s_barrier
	s_setprio 1
	v_mfma_f32_16x16x32_bf16 v[126:129], v[148:151], v[202:205], v[126:129]
	v_mfma_f32_16x16x32_bf16 v[122:125], v[156:159], v[202:205], v[122:125]
	v_mfma_f32_16x16x32_bf16 v[110:113], v[148:151], v[212:215], v[110:113]
	v_mfma_f32_16x16x32_bf16 v[106:109], v[156:159], v[212:215], v[106:109]
	v_mfma_f32_16x16x32_bf16 v[94:97], v[148:151], v[220:223], v[94:97]
	v_mfma_f32_16x16x32_bf16 v[90:93], v[156:159], v[220:223], v[90:93]
	v_mfma_f32_16x16x32_bf16 v[78:81], v[148:151], v[228:231], v[78:81]
	v_mfma_f32_16x16x32_bf16 v[74:77], v[156:159], v[228:231], v[74:77]
	v_mfma_f32_16x16x32_bf16 v[126:129], v[152:155], v[208:211], v[126:129]
	v_mfma_f32_16x16x32_bf16 v[122:125], v[160:163], v[208:211], v[122:125]
	v_mfma_f32_16x16x32_bf16 v[110:113], v[152:155], v[216:219], v[110:113]
	v_mfma_f32_16x16x32_bf16 v[106:109], v[160:163], v[216:219], v[106:109]
	v_mfma_f32_16x16x32_bf16 v[94:97], v[152:155], v[224:227], v[94:97]
	v_mfma_f32_16x16x32_bf16 v[90:93], v[160:163], v[224:227], v[90:93]
	v_mfma_f32_16x16x32_bf16 v[78:81], v[152:155], v[232:235], v[78:81]
	v_mfma_f32_16x16x32_bf16 v[74:77], v[160:163], v[232:235], v[74:77]
	s_setprio 0
	s_barrier
	s_add_i32 s83, s82, -3
	s_cmp_lt_u32 s83, s79
	s_cbranch_scc1 .Lkq_1_loop
	s_branch .Lkq_exit
.Lkq_2:
	s_waitcnt vmcnt(0)
	s_barrier
	s_mov_b64 s[76:77], s[48:49]
	s_add_u32 vcc_lo, s80, 0xffffff80
	s_addc_u32 vcc_hi, s81, -1
	s_add_u32 s76, s76, s10
	s_addc_u32 s77, s77, 0
	v_lshl_add_u64 v[136:137], s[76:77], 0, v[0:1]
	s_add_i32 m0, s94, 0xc000
	v_lshl_add_u64 v[144:145], s[76:77], 0, v[130:131]
	global_load_lds_dwordx4 v[136:137], off
	s_add_i32 m0, s94, 0xe000
	s_nop 0
	global_load_lds_dwordx4 v[144:145], off
	s_add_u32 s76, s76, 0x80
	s_addc_u32 s77, s77, 0
	s_add_u32 vcc_lo, vcc_lo, 0x80
	s_addc_u32 vcc_hi, vcc_hi, 0
	v_lshl_add_u64 v[136:137], s[76:77], 0, v[0:1]
	s_add_i32 m0, s94, 0x0
	v_lshl_add_u64 v[144:145], s[76:77], 0, v[130:131]
	global_load_lds_dwordx4 v[136:137], off
	s_add_i32 m0, s94, 0x2000
	s_nop 0
	global_load_lds_dwordx4 v[144:145], off
	v_lshl_add_u64 v[182:183], vcc, 0, v[0:1]
	s_add_i32 m0, s93, 0x14000
	v_lshl_add_u64 v[236:237], vcc, 0, v[130:131]
	global_load_lds_dwordx4 v[182:183], off
	s_add_i32 m0, s93, 0x16000
	s_nop 0
	global_load_lds_dwordx4 v[236:237], off
	s_add_u32 s76, s76, 0x80
	s_addc_u32 s77, s77, 0
	s_add_u32 vcc_lo, vcc_lo, 0x80
	s_addc_u32 vcc_hi, vcc_hi, 0
	s_mov_b32 s82, 3
	s_add_i32 s59, s79, -1
; #define PG8_STAGE(bufoff, gbase, voff) do { _Pragma("unroll") for (int _i = 0; _i < 2; ++_i) \
;         __builtin_amdgcn_global_load_lds((const unsigned*)((const char*)(gbase) + (voff)[_i]), (PG8_LAS unsigned*)(lds + (bufoff) + ldsw + _i * 8192), 16, 0, 0); } while (0)
; #define PG8_LDA(dst, b, h) do { _Pragma("unroll") for (int m = 0; m < 4; ++m) _Pragma("unroll") for (int k = 0; k < 2; ++k) dst[m][k] = *(const PG8_LAS bf16x8*)(lds + PG8_SA(b, h) + aoff + m * 2048 + k * 1024); } while (0)
; #define PG8_LDB(dst, b, h) do { _Pragma("unroll") for (int n = 0; n < 2; ++n) _Pragma("unroll") for (int k = 0; k < 2; ++k) dst[n][k] = *(const PG8_LAS bf16x8*)(lds + PG8_SB(b, h) + boff + n * 2048 + k * 1024); } while (0)
; template <class Epi, class Sched, bool ALIGN_EPI = false, bool SP2 = false>
; __device__ __forceinline__ void gemm_phase(PG8_LAS unsigned char* lds, const Gemm g, const Sched& S, const Epi& E) {
;     ...
;         for (int t = 0; t < nt; t += 2) {
;             const bool last = (t == nt - 2);
;             const char* a1 = cA + (size_t)(t + 1) * kstep;
;             const char* a2 = last ? nA : cA + (size_t)(t + 2) * kstep; const char* b2 = last ? nB : cB + (size_t)(t + 2) * kstep;
;             const char* a3 = a2 + kstep; const char* b3 = b2 + kstep;
;             if (last && has_next) S.a_ready(nxt);
;             if constexpr (SP2) {
;             PG8_LDB(B0, 0, 0); PG8_LDB(B1, 0, 1); PG8_SCHED; PG8_LDA(At, 0, 0); PG8_STAGE(PG8_SA(1, 1), a1 + hstep, voffA);
;             PG8_WAIT_V(8); PG8_WAIT_L(0); PG8_BAR; PG8_MMA(0, 0, At, B0); PG8_MMA(0, 1, At, B1); PG8_BAR; PG8_SCHED;
;             PG8_LDA(At, 0, 1); PG8_STAGE(PG8_SB(0, 0), b2, voffB); PG8_STAGE(PG8_SB(0, 1), b2 + hstep, voffB); PG8_STAGE(PG8_SA(0, 0), a2, voffA);
;             PG8_WAIT_V(8); PG8_WAIT_L(0); PG8_BAR; PG8_MMA(1, 0, At, B0); PG8_MMA(1, 1, At, B1); PG8_BAR; PG8_SCHED;
;             PG8_LDB(B0, 1, 0); PG8_LDB(B1, 1, 1); PG8_SCHED; PG8_LDA(At, 1, 0); PG8_STAGE(PG8_SA(0, 1), a2 + hstep, voffA);
;             PG8_WAIT_V(8); PG8_WAIT_L(0); PG8_BAR; PG8_MMA(0, 0, At, B0); PG8_MMA(0, 1, At, B1); PG8_BAR; PG8_SCHED;
;             PG8_LDA(At, 1, 1); PG8_STAGE(PG8_SB(1, 0), b3, voffB); PG8_STAGE(PG8_SB(1, 1), b3 + hstep, voffB); PG8_STAGE(PG8_SA(1, 0), a3, voffA);
;             PG8_WAIT_V(8); PG8_WAIT_L(0); PG8_BAR; PG8_MMA(1, 0, At, B0); PG8_MMA(1, 1, At, B1); PG8_BAR; PG8_SCHED;
.Lkq_2_loop:
	v_add_u32_e32 v136, 0x10000, v147
	ds_read_b128 v[148:151], v136
	ds_read_b128 v[152:155], v136 offset:1024
	ds_read_b128 v[156:159], v136 offset:2048
	ds_read_b128 v[160:163], v136 offset:3072
	ds_read_b128 v[202:205], v165 offset:16384
	ds_read_b128 v[208:211], v165 offset:17408
	ds_read_b128 v[212:215], v165 offset:18432
	ds_read_b128 v[216:219], v165 offset:19456
	ds_read_b128 v[220:223], v165 offset:20480
	ds_read_b128 v[224:227], v165 offset:21504
	ds_read_b128 v[228:231], v165 offset:22528
	ds_read_b128 v[232:235], v165 offset:23552
	v_lshl_add_u64 v[136:137], s[76:77], 0, v[0:1]
	s_add_i32 m0, s94, 0x8000
	v_lshl_add_u64 v[144:145], s[76:77], 0, v[130:131]
	global_load_lds_dwordx4 v[136:137], off
	s_add_i32 m0, s94, 0xa000
	s_nop 0
	global_load_lds_dwordx4 v[144:145], off
	v_lshl_add_u64 v[182:183], vcc, 0, v[0:1]
	s_add_i32 m0, s93, 0x1c000
	v_lshl_add_u64 v[236:237], vcc, 0, v[130:131]
	global_load_lds_dwordx4 v[182:183], off
	s_add_i32 m0, s93, 0x1e000
	s_nop 0
	global_load_lds_dwordx4 v[236:237], off
	s_cmp_lt_u32 s82, s59
	s_cselect_b32 s83, 0x80, 0
	s_add_u32 s76, s76, s83
	s_addc_u32 s77, s77, 0
	s_add_u32 vcc_lo, vcc_lo, s83
	s_addc_u32 vcc_hi, vcc_hi, 0
	s_add_i32 s82, s82, 1
	s_waitcnt vmcnt(8)
	s_waitcnt lgkmcnt(0)
	s_barrier
	s_setprio 1
	v_mfma_f32_16x16x32_bf16 v[62:65], v[148:151], v[202:205], v[62:65]
	v_mfma_f32_16x16x32_bf16 v[58:61], v[156:159], v[202:205], v[58:61]
	v_mfma_f32_16x16x32_bf16 v[46:49], v[148:151], v[212:215], v[46:49]
	v_mfma_f32_16x16x32_bf16 v[42:45], v[156:159], v[212:215], v[42:45]
	v_mfma_f32_16x16x32_bf16 v[30:33], v[148:151], v[220:223], v[30:33]
	v_mfma_f32_16x16x32_bf16 v[26:29], v[156:159], v[220:223], v[26:29]
	v_mfma_f32_16x16x32_bf16 v[14:17], v[148:151], v[228:231], v[14:17]
	v_mfma_f32_16x16x32_bf16 v[10:13], v[156:159], v[228:231], v[10:13]
	v_mfma_f32_16x16x32_bf16 v[62:65], v[152:155], v[208:211], v[62:65]
	v_mfma_f32_16x16x32_bf16 v[58:61], v[160:163], v[208:211], v[58:61]
	v_mfma_f32_16x16x32_bf16 v[46:49], v[152:155], v[216:219], v[46:49]
	v_mfma_f32_16x16x32_bf16 v[42:45], v[160:163], v[216:219], v[42:45]
	v_mfma_f32_16x16x32_bf16 v[30:33], v[152:155], v[224:227], v[30:33]
	v_mfma_f32_16x16x32_bf16 v[26:29], v[160:163], v[224:227], v[26:29]
	v_mfma_f32_16x16x32_bf16 v[14:17], v[152:155], v[232:235], v[14:17]
	v_mfma_f32_16x16x32_bf16 v[10:13], v[160:163], v[232:235], v[10:13]
	s_setprio 0
	s_barrier
	v_add_u32_e32 v136, 0x18000, v147
	ds_read_b128 v[148:151], v136
	ds_read_b128 v[152:155], v136 offset:1024
	ds_read_b128 v[156:159], v136 offset:2048
	ds_read_b128 v[160:163], v136 offset:3072
	ds_read_b128 v[202:205], v165 offset:49152
	ds_read_b128 v[208:211], v165 offset:50176
	ds_read_b128 v[212:215], v165 offset:51200
	ds_read_b128 v[216:219], v165 offset:52224
	ds_read_b128 v[220:223], v165 offset:53248
	ds_read_b128 v[224:227], v165 offset:54272
	ds_read_b128 v[228:231], v165 offset:55296
	ds_read_b128 v[232:235], v165 offset:56320
	v_lshl_add_u64 v[136:137], s[76:77], 0, v[0:1]
	s_add_i32 m0, s94, 0x4000
	v_lshl_add_u64 v[144:145], s[76:77], 0, v[130:131]
	global_load_lds_dwordx4 v[136:137], off
	s_add_i32 m0, s94, 0x6000
	s_nop 0
	global_load_lds_dwordx4 v[144:145], off
	v_lshl_add_u64 v[182:183], vcc, 0, v[0:1]
	s_add_i32 m0, s93, 0x10000
	v_lshl_add_u64 v[236:237], vcc, 0, v[130:131]
	global_load_lds_dwordx4 v[182:183], off
	s_add_i32 m0, s93, 0x12000
	s_nop 0
	global_load_lds_dwordx4 v[236:237], off
	s_cmp_lt_u32 s82, s59
	s_cselect_b32 s83, 0x80, 0
	s_add_u32 s76, s76, s83
	s_addc_u32 s77, s77, 0
	s_add_u32 vcc_lo, vcc_lo, s83
	s_addc_u32 vcc_hi, vcc_hi, 0
	s_add_i32 s82, s82, 1
	s_waitcnt vmcnt(8)
	s_waitcnt lgkmcnt(0)
	s_barrier
	s_setprio 1
	v_mfma_f32_16x16x32_bf16 v[62:65], v[148:151], v[202:205], v[62:65]
	v_mfma_f32_16x16x32_bf16 v[58:61], v[156:159], v[202:205], v[58:61]
	v_mfma_f32_16x16x32_bf16 v[46:49], v[148:151], v[212:215], v[46:49]
	v_mfma_f32_16x16x32_bf16 v[42:45], v[156:159], v[212:215], v[42:45]
	v_mfma_f32_16x16x32_bf16 v[30:33], v[148:151], v[220:223], v[30:33]
	v_mfma_f32_16x16x32_bf16 v[26:29], v[156:159], v[220:223], v[26:29]
	v_mfma_f32_16x16x32_bf16 v[14:17], v[148:151], v[228:231], v[14:17]
	v_mfma_f32_16x16x32_bf16 v[10:13], v[156:159], v[228:231], v[10:13]
	v_mfma_f32_16x16x32_bf16 v[62:65], v[152:155], v[208:211], v[62:65]
	v_mfma_f32_16x16x32_bf16 v[58:61], v[160:163], v[208:211], v[58:61]
	v_mfma_f32_16x16x32_bf16 v[46:49], v[152:155], v[216:219], v[46:49]
	v_mfma_f32_16x16x32_bf16 v[42:45], v[160:163], v[216:219], v[42:45]
	v_mfma_f32_16x16x32_bf16 v[30:33], v[152:155], v[224:227], v[30:33]
	v_mfma_f32_16x16x32_bf16 v[26:29], v[160:163], v[224:227], v[26:29]
	v_mfma_f32_16x16x32_bf16 v[14:17], v[152:155], v[232:235], v[14:17]
	v_mfma_f32_16x16x32_bf16 v[10:13], v[160:163], v[232:235], v[10:13]
	s_setprio 0
	s_barrier
	v_add_u32_e32 v136, 0x14000, v147
	ds_read_b128 v[148:151], v136
	ds_read_b128 v[152:155], v136 offset:1024
	ds_read_b128 v[156:159], v136 offset:2048
	ds_read_b128 v[160:163], v136 offset:3072
	ds_read_b128 v[202:205], v165
	ds_read_b128 v[208:211], v165 offset:1024
	ds_read_b128 v[212:215], v165 offset:2048
	ds_read_b128 v[216:219], v165 offset:3072
	ds_read_b128 v[220:223], v165 offset:4096
	ds_read_b128 v[224:227], v165 offset:5120
	ds_read_b128 v[228:231], v165 offset:6144
	ds_read_b128 v[232:235], v165 offset:7168
	v_lshl_add_u64 v[136:137], s[76:77], 0, v[0:1]
	s_add_i32 m0, s94, 0xc000
	v_lshl_add_u64 v[144:145], s[76:77], 0, v[130:131]
	global_load_lds_dwordx4 v[136:137], off
	s_add_i32 m0, s94, 0xe000
	s_nop 0
	global_load_lds_dwordx4 v[144:145], off
	v_lshl_add_u64 v[182:183], vcc, 0, v[0:1]
	s_add_i32 m0, s93, 0x18000
	v_lshl_add_u64 v[236:237], vcc, 0, v[130:131]
	global_load_lds_dwordx4 v[182:183], off
	s_add_i32 m0, s93, 0x1a000
	s_nop 0
	global_load_lds_dwordx4 v[236:237], off
	s_cmp_lt_u32 s82, s59
	s_cselect_b32 s83, 0x80, 0
	s_add_u32 s76, s76, s83
	s_addc_u32 s77, s77, 0
	s_add_u32 vcc_lo, vcc_lo, s83
	s_addc_u32 vcc_hi, vcc_hi, 0
	s_add_i32 s82, s82, 1
	s_waitcnt vmcnt(8)
	s_waitcnt lgkmcnt(0)
	s_barrier
; #define PG8_STAGE(bufoff, gbase, voff) do { _Pragma("unroll") for (int _i = 0; _i < 2; ++_i) \
;         __builtin_amdgcn_global_load_lds((const unsigned*)((const char*)(gbase) + (voff)[_i]), (PG8_LAS unsigned*)(lds + (bufoff) + ldsw + _i * 8192), 16, 0, 0); } while (0)
; #define PG8_LDA(dst, b, h) do { _Pragma("unroll") for (int m = 0; m < 4; ++m) _Pragma("unroll") for (int k = 0; k < 2; ++k) dst[m][k] = *(const PG8_LAS bf16x8*)(lds + PG8_SA(b, h) + aoff + m * 2048 + k * 1024); } while (0)
; #define PG8_LDB(dst, b, h) do { _Pragma("unroll") for (int n = 0; n < 2; ++n) _Pragma("unroll") for (int k = 0; k < 2; ++k) dst[n][k] = *(const PG8_LAS bf16x8*)(lds + PG8_SB(b, h) + boff + n * 2048 + k * 1024); } while (0)
; template <class Epi, class Sched, bool ALIGN_EPI = false, bool SP2 = false>
; __device__ __forceinline__ void gemm_phase(PG8_LAS unsigned char* lds, const Gemm g, const Sched& S, const Epi& E) {
;     ...
;         for (int t = 0; t < nt; t += 2) {
;             const bool last = (t == nt - 2);
;             const char* a1 = cA + (size_t)(t + 1) * kstep;
;             const char* a2 = last ? nA : cA + (size_t)(t + 2) * kstep; const char* b2 = last ? nB : cB + (size_t)(t + 2) * kstep;
;             const char* a3 = a2 + kstep; const char* b3 = b2 + kstep;
;             if (last && has_next) S.a_ready(nxt);
;             if constexpr (SP2) {
;             PG8_LDB(B0, 0, 0); PG8_LDB(B1, 0, 1); PG8_SCHED; PG8_LDA(At, 0, 0); PG8_STAGE(PG8_SA(1, 1), a1 + hstep, voffA);
;             PG8_WAIT_V(8); PG8_WAIT_L(0); PG8_BAR; PG8_MMA(0, 0, At, B0); PG8_MMA(0, 1, At, B1); PG8_BAR; PG8_SCHED;
;             PG8_LDA(At, 0, 1); PG8_STAGE(PG8_SB(0, 0), b2, voffB); PG8_STAGE(PG8_SB(0, 1), b2 + hstep, voffB); PG8_STAGE(PG8_SA(0, 0), a2, voffA);
;             PG8_WAIT_V(8); PG8_WAIT_L(0); PG8_BAR; PG8_MMA(1, 0, At, B0); PG8_MMA(1, 1, At, B1); PG8_BAR; PG8_SCHED;
;             PG8_LDB(B0, 1, 0); PG8_LDB(B1, 1, 1); PG8_SCHED; PG8_LDA(At, 1, 0); PG8_STAGE(PG8_SA(0, 1), a2 + hstep, voffA);
;             PG8_WAIT_V(8); PG8_WAIT_L(0); PG8_BAR; PG8_MMA(0, 0, At, B0); PG8_MMA(0, 1, At, B1); PG8_BAR; PG8_SCHED;
;             PG8_LDA(At, 1, 1); PG8_STAGE(PG8_SB(1, 0), b3, voffB); PG8_STAGE(PG8_SB(1, 1), b3 + hstep, voffB); PG8_STAGE(PG8_SA(1, 0), a3, voffA);
;             PG8_WAIT_V(8); PG8_WAIT_L(0); PG8_BAR; PG8_MMA(1, 0, At, B0); PG8_MMA(1, 1, At, B1); PG8_BAR; PG8_SCHED;
	s_setprio 1
	v_mfma_f32_16x16x32_bf16 v[62:65], v[148:151], v[202:205], v[62:65]
	v_mfma_f32_16x16x32_bf16 v[58:61], v[156:159], v[202:205], v[58:61]
	v_mfma_f32_16x16x32_bf16 v[46:49], v[148:151], v[212:215], v[46:49]
	v_mfma_f32_16x16x32_bf16 v[42:45], v[156:159], v[212:215], v[42:45]
	v_mfma_f32_16x16x32_bf16 v[30:33], v[148:151], v[220:223], v[30:33]
	v_mfma_f32_16x16x32_bf16 v[26:29], v[156:159], v[220:223], v[26:29]
	v_mfma_f32_16x16x32_bf16 v[14:17], v[148:151], v[228:231], v[14:17]
	v_mfma_f32_16x16x32_bf16 v[10:13], v[156:159], v[228:231], v[10:13]
	v_mfma_f32_16x16x32_bf16 v[62:65], v[152:155], v[208:211], v[62:65]
	v_mfma_f32_16x16x32_bf16 v[58:61], v[160:163], v[208:211], v[58:61]
	v_mfma_f32_16x16x32_bf16 v[46:49], v[152:155], v[216:219], v[46:49]
	v_mfma_f32_16x16x32_bf16 v[42:45], v[160:163], v[216:219], v[42:45]
	v_mfma_f32_16x16x32_bf16 v[30:33], v[152:155], v[224:227], v[30:33]
	v_mfma_f32_16x16x32_bf16 v[26:29], v[160:163], v[224:227], v[26:29]
	v_mfma_f32_16x16x32_bf16 v[14:17], v[152:155], v[232:235], v[14:17]
	v_mfma_f32_16x16x32_bf16 v[10:13], v[160:163], v[232:235], v[10:13]
	s_setprio 0
	s_barrier
	v_add_u32_e32 v136, 0x1c000, v147
	ds_read_b128 v[148:151], v136
	ds_read_b128 v[152:155], v136 offset:1024
	ds_read_b128 v[156:159], v136 offset:2048
	ds_read_b128 v[160:163], v136 offset:3072
	ds_read_b128 v[202:205], v165 offset:32768
	ds_read_b128 v[208:211], v165 offset:33792
	ds_read_b128 v[212:215], v165 offset:34816
	ds_read_b128 v[216:219], v165 offset:35840
	ds_read_b128 v[220:223], v165 offset:36864
	ds_read_b128 v[224:227], v165 offset:37888
	ds_read_b128 v[228:231], v165 offset:38912
	ds_read_b128 v[232:235], v165 offset:39936
	v_lshl_add_u64 v[136:137], s[76:77], 0, v[0:1]
	s_add_i32 m0, s94, 0x0
	v_lshl_add_u64 v[144:145], s[76:77], 0, v[130:131]
	global_load_lds_dwordx4 v[136:137], off
	s_add_i32 m0, s94, 0x2000
	s_nop 0
	global_load_lds_dwordx4 v[144:145], off
	v_lshl_add_u64 v[182:183], vcc, 0, v[0:1]
	s_add_i32 m0, s93, 0x14000
	v_lshl_add_u64 v[236:237], vcc, 0, v[130:131]
	global_load_lds_dwordx4 v[182:183], off
	s_add_i32 m0, s93, 0x16000
	s_nop 0
	global_load_lds_dwordx4 v[236:237], off
	s_cmp_lt_u32 s82, s59
	s_cselect_b32 s83, 0x80, 0
	s_add_u32 s76, s76, s83
	s_addc_u32 s77, s77, 0
	s_add_u32 vcc_lo, vcc_lo, s83
	s_addc_u32 vcc_hi, vcc_hi, 0
	s_add_i32 s82, s82, 1
	s_waitcnt vmcnt(8)
	s_waitcnt lgkmcnt(0)
	s_barrier
	s_setprio 1
	v_mfma_f32_16x16x32_bf16 v[62:65], v[148:151], v[202:205], v[62:65]
	v_mfma_f32_16x16x32_bf16 v[58:61], v[156:159], v[202:205], v[58:61]
	v_mfma_f32_16x16x32_bf16 v[46:49], v[148:151], v[212:215], v[46:49]
	v_mfma_f32_16x16x32_bf16 v[42:45], v[156:159], v[212:215], v[42:45]
	v_mfma_f32_16x16x32_bf16 v[30:33], v[148:151], v[220:223], v[30:33]
	v_mfma_f32_16x16x32_bf16 v[26:29], v[156:159], v[220:223], v[26:29]
	v_mfma_f32_16x16x32_bf16 v[14:17], v[148:151], v[228:231], v[14:17]
	v_mfma_f32_16x16x32_bf16 v[10:13], v[156:159], v[228:231], v[10:13]
	v_mfma_f32_16x16x32_bf16 v[62:65], v[152:155], v[208:211], v[62:65]
	v_mfma_f32_16x16x32_bf16 v[58:61], v[160:163], v[208:211], v[58:61]
	v_mfma_f32_16x16x32_bf16 v[46:49], v[152:155], v[216:219], v[46:49]
	v_mfma_f32_16x16x32_bf16 v[42:45], v[160:163], v[216:219], v[42:45]
	v_mfma_f32_16x16x32_bf16 v[30:33], v[152:155], v[224:227], v[30:33]
	v_mfma_f32_16x16x32_bf16 v[26:29], v[160:163], v[224:227], v[26:29]
	v_mfma_f32_16x16x32_bf16 v[14:17], v[152:155], v[232:235], v[14:17]
	v_mfma_f32_16x16x32_bf16 v[10:13], v[160:163], v[232:235], v[10:13]
	s_setprio 0
	s_barrier
	s_add_i32 s83, s82, -3
	s_cmp_lt_u32 s83, s79
	s_cbranch_scc1 .Lkq_2_loop
	s_branch .Lkq_exit
.Lkq_3:
	s_waitcnt vmcnt(0)
	s_barrier
	s_mov_b64 s[76:77], s[48:49]
	s_add_u32 vcc_lo, s80, 0xffffff80
	s_addc_u32 vcc_hi, s81, -1
	s_add_u32 vcc_lo, vcc_lo, s10
	s_addc_u32 vcc_hi, vcc_hi, 0
	s_add_u32 s76, s76, 0x80
	s_addc_u32 s77, s77, 0
	s_add_u32 vcc_lo, vcc_lo, 0x80
	s_addc_u32 vcc_hi, vcc_hi, 0
	v_lshl_add_u64 v[136:137], s[76:77], 0, v[0:1]
	s_add_i32 m0, s94, 0x4000
	v_lshl_add_u64 v[144:145], s[76:77], 0, v[130:131]
	global_load_lds_dwordx4 v[136:137], off
	s_add_i32 m0, s94, 0x6000
	s_nop 0
	global_load_lds_dwordx4 v[144:145], off
	v_lshl_add_u64 v[182:183], vcc, 0, v[0:1]
	s_add_i32 m0, s93, 0x10000
	v_lshl_add_u64 v[236:237], vcc, 0, v[130:131]
	global_load_lds_dwordx4 v[182:183], off
	s_add_i32 m0, s93, 0x12000
	s_nop 0
	global_load_lds_dwordx4 v[236:237], off
	s_add_u32 s76, s76, 0x80
	s_addc_u32 s77, s77, 0
	s_add_u32 vcc_lo, vcc_lo, 0x80
	s_addc_u32 vcc_hi, vcc_hi, 0
	s_mov_b32 s82, 3
	s_add_i32 s59, s79, -1
; #define PG8_STAGE(bufoff, gbase, voff) do { _Pragma("unroll") for (int _i = 0; _i < 2; ++_i) \
;         __builtin_amdgcn_global_load_lds((const unsigned*)((const char*)(gbase) + (voff)[_i]), (PG8_LAS unsigned*)(lds + (bufoff) + ldsw + _i * 8192), 16, 0, 0); } while (0)
; #define PG8_LDA(dst, b, h) do { _Pragma("unroll") for (int m = 0; m < 4; ++m) _Pragma("unroll") for (int k = 0; k < 2; ++k) dst[m][k] = *(const PG8_LAS bf16x8*)(lds + PG8_SA(b, h) + aoff + m * 2048 + k * 1024); } while (0)
; #define PG8_LDB(dst, b, h) do { _Pragma("unroll") for (int n = 0; n < 2; ++n) _Pragma("unroll") for (int k = 0; k < 2; ++k) dst[n][k] = *(const PG8_LAS bf16x8*)(lds + PG8_SB(b, h) + boff + n * 2048 + k * 1024); } while (0)
; template <class Epi, class Sched, bool ALIGN_EPI = false, bool SP2 = false>
; __device__ __forceinline__ void gemm_phase(PG8_LAS unsigned char* lds, const Gemm g, const Sched& S, const Epi& E) {
;     ...
;         for (int t = 0; t < nt; t += 2) {
;             const bool last = (t == nt - 2);
;             const char* a1 = cA + (size_t)(t + 1) * kstep;
;             const char* a2 = last ? nA : cA + (size_t)(t + 2) * kstep; const char* b2 = last ? nB : cB + (size_t)(t + 2) * kstep;
;             const char* a3 = a2 + kstep; const char* b3 = b2 + kstep;
;             if (last && has_next) S.a_ready(nxt);
;             if constexpr (SP2) {
;             PG8_LDB(B0, 0, 0); PG8_LDB(B1, 0, 1); PG8_SCHED; PG8_LDA(At, 0, 0); PG8_STAGE(PG8_SA(1, 1), a1 + hstep, voffA);
;             PG8_WAIT_V(8); PG8_WAIT_L(0); PG8_BAR; PG8_MMA(0, 0, At, B0); PG8_MMA(0, 1, At, B1); PG8_BAR; PG8_SCHED;
;             PG8_LDA(At, 0, 1); PG8_STAGE(PG8_SB(0, 0), b2, voffB); PG8_STAGE(PG8_SB(0, 1), b2 + hstep, voffB); PG8_STAGE(PG8_SA(0, 0), a2, voffA);
;             PG8_WAIT_V(8); PG8_WAIT_L(0); PG8_BAR; PG8_MMA(1, 0, At, B0); PG8_MMA(1, 1, At, B1); PG8_BAR; PG8_SCHED;
;             PG8_LDB(B0, 1, 0); PG8_LDB(B1, 1, 1); PG8_SCHED; PG8_LDA(At, 1, 0); PG8_STAGE(PG8_SA(0, 1), a2 + hstep, voffA);
;             PG8_WAIT_V(8); PG8_WAIT_L(0); PG8_BAR; PG8_MMA(0, 0, At, B0); PG8_MMA(0, 1, At, B1); PG8_BAR; PG8_SCHED;
;             PG8_LDA(At, 1, 1); PG8_STAGE(PG8_SB(1, 0), b3, voffB); PG8_STAGE(PG8_SB(1, 1), b3 + hstep, voffB); PG8_STAGE(PG8_SA(1, 0), a3, voffA);
;             PG8_WAIT_V(8); PG8_WAIT_L(0); PG8_BAR; PG8_MMA(1, 0, At, B0); PG8_MMA(1, 1, At, B1); PG8_BAR; PG8_SCHED;
.Lkq_3_loop:
	v_add_u32_e32 v136, 0x14000, v147
	ds_read_b128 v[166:169], v136
	ds_read_b128 v[170:173], v136 offset:1024
	ds_read_b128 v[174:177], v136 offset:2048
	ds_read_b128 v[178:181], v136 offset:3072
	ds_read_b128 v[202:205], v165
	ds_read_b128 v[208:211], v165 offset:1024
	ds_read_b128 v[212:215], v165 offset:2048
	ds_read_b128 v[216:219], v165 offset:3072
	ds_read_b128 v[220:223], v165 offset:4096
	ds_read_b128 v[224:227], v165 offset:5120
	ds_read_b128 v[228:231], v165 offset:6144
	ds_read_b128 v[232:235], v165 offset:7168
	v_lshl_add_u64 v[136:137], s[76:77], 0, v[0:1]
	s_add_i32 m0, s94, 0xc000
	v_lshl_add_u64 v[144:145], s[76:77], 0, v[130:131]
	global_load_lds_dwordx4 v[136:137], off
	s_add_i32 m0, s94, 0xe000
	s_nop 0
	global_load_lds_dwordx4 v[144:145], off
	v_lshl_add_u64 v[182:183], vcc, 0, v[0:1]
	s_add_i32 m0, s93, 0x18000
	v_lshl_add_u64 v[236:237], vcc, 0, v[130:131]
	global_load_lds_dwordx4 v[182:183], off
	s_add_i32 m0, s93, 0x1a000
	s_nop 0
	global_load_lds_dwordx4 v[236:237], off
	s_cmp_lt_u32 s82, s59
	s_cselect_b32 s83, 0x80, 0
	s_add_u32 s76, s76, s83
	s_addc_u32 s77, s77, 0
	s_add_u32 vcc_lo, vcc_lo, s83
	s_addc_u32 vcc_hi, vcc_hi, 0
	s_add_i32 s82, s82, 1
	s_waitcnt vmcnt(8)
	s_waitcnt lgkmcnt(0)
	s_barrier
	s_setprio 1
	v_mfma_f32_16x16x32_bf16 v[118:121], v[166:169], v[202:205], v[118:121]
	v_mfma_f32_16x16x32_bf16 v[114:117], v[174:177], v[202:205], v[114:117]
	v_mfma_f32_16x16x32_bf16 v[102:105], v[166:169], v[212:215], v[102:105]
	v_mfma_f32_16x16x32_bf16 v[98:101], v[174:177], v[212:215], v[98:101]
	v_mfma_f32_16x16x32_bf16 v[86:89], v[166:169], v[220:223], v[86:89]
	v_mfma_f32_16x16x32_bf16 v[82:85], v[174:177], v[220:223], v[82:85]
	v_mfma_f32_16x16x32_bf16 v[70:73], v[166:169], v[228:231], v[70:73]
	v_mfma_f32_16x16x32_bf16 v[66:69], v[174:177], v[228:231], v[66:69]
	v_mfma_f32_16x16x32_bf16 v[118:121], v[170:173], v[208:211], v[118:121]
	v_mfma_f32_16x16x32_bf16 v[114:117], v[178:181], v[208:211], v[114:117]
	v_mfma_f32_16x16x32_bf16 v[102:105], v[170:173], v[216:219], v[102:105]
	v_mfma_f32_16x16x32_bf16 v[98:101], v[178:181], v[216:219], v[98:101]
	v_mfma_f32_16x16x32_bf16 v[86:89], v[170:173], v[224:227], v[86:89]
	v_mfma_f32_16x16x32_bf16 v[82:85], v[178:181], v[224:227], v[82:85]
	v_mfma_f32_16x16x32_bf16 v[70:73], v[170:173], v[232:235], v[70:73]
	v_mfma_f32_16x16x32_bf16 v[66:69], v[178:181], v[232:235], v[66:69]
	s_setprio 0
	s_barrier
	v_add_u32_e32 v136, 0x1c000, v147
	ds_read_b128 v[166:169], v136
	ds_read_b128 v[170:173], v136 offset:1024
	ds_read_b128 v[174:177], v136 offset:2048
	ds_read_b128 v[178:181], v136 offset:3072
	ds_read_b128 v[202:205], v165 offset:32768
	ds_read_b128 v[208:211], v165 offset:33792
	ds_read_b128 v[212:215], v165 offset:34816
	ds_read_b128 v[216:219], v165 offset:35840
	ds_read_b128 v[220:223], v165 offset:36864
	ds_read_b128 v[224:227], v165 offset:37888
	ds_read_b128 v[228:231], v165 offset:38912
	ds_read_b128 v[232:235], v165 offset:39936
	v_lshl_add_u64 v[136:137], s[76:77], 0, v[0:1]
	s_add_i32 m0, s94, 0x0
	v_lshl_add_u64 v[144:145], s[76:77], 0, v[130:131]
	global_load_lds_dwordx4 v[136:137], off
	s_add_i32 m0, s94, 0x2000
	s_nop 0
	global_load_lds_dwordx4 v[144:145], off
	v_lshl_add_u64 v[182:183], vcc, 0, v[0:1]
	s_add_i32 m0, s93, 0x14000
	v_lshl_add_u64 v[236:237], vcc, 0, v[130:131]
	global_load_lds_dwordx4 v[182:183], off
	s_add_i32 m0, s93, 0x16000
	s_nop 0
	global_load_lds_dwordx4 v[236:237], off
	s_cmp_lt_u32 s82, s59
	s_cselect_b32 s83, 0x80, 0
	s_add_u32 s76, s76, s83
	s_addc_u32 s77, s77, 0
	s_add_u32 vcc_lo, vcc_lo, s83
	s_addc_u32 vcc_hi, vcc_hi, 0
	s_add_i32 s82, s82, 1
	s_waitcnt vmcnt(8)
	s_waitcnt lgkmcnt(0)
	s_barrier
	s_setprio 1
	v_mfma_f32_16x16x32_bf16 v[118:121], v[166:169], v[202:205], v[118:121]
	v_mfma_f32_16x16x32_bf16 v[114:117], v[174:177], v[202:205], v[114:117]
	v_mfma_f32_16x16x32_bf16 v[102:105], v[166:169], v[212:215], v[102:105]
	v_mfma_f32_16x16x32_bf16 v[98:101], v[174:177], v[212:215], v[98:101]
	v_mfma_f32_16x16x32_bf16 v[86:89], v[166:169], v[220:223], v[86:89]
	v_mfma_f32_16x16x32_bf16 v[82:85], v[174:177], v[220:223], v[82:85]
	v_mfma_f32_16x16x32_bf16 v[70:73], v[166:169], v[228:231], v[70:73]
	v_mfma_f32_16x16x32_bf16 v[66:69], v[174:177], v[228:231], v[66:69]
	v_mfma_f32_16x16x32_bf16 v[118:121], v[170:173], v[208:211], v[118:121]
	v_mfma_f32_16x16x32_bf16 v[114:117], v[178:181], v[208:211], v[114:117]
	v_mfma_f32_16x16x32_bf16 v[102:105], v[170:173], v[216:219], v[102:105]
	v_mfma_f32_16x16x32_bf16 v[98:101], v[178:181], v[216:219], v[98:101]
	v_mfma_f32_16x16x32_bf16 v[86:89], v[170:173], v[224:227], v[86:89]
	v_mfma_f32_16x16x32_bf16 v[82:85], v[178:181], v[224:227], v[82:85]
	v_mfma_f32_16x16x32_bf16 v[70:73], v[170:173], v[232:235], v[70:73]
	v_mfma_f32_16x16x32_bf16 v[66:69], v[178:181], v[232:235], v[66:69]
	s_setprio 0
	s_barrier
	v_add_u32_e32 v136, 0x10000, v147
	ds_read_b128 v[166:169], v136
	ds_read_b128 v[170:173], v136 offset:1024
	ds_read_b128 v[174:177], v136 offset:2048
	ds_read_b128 v[178:181], v136 offset:3072
	ds_read_b128 v[202:205], v165 offset:16384
	ds_read_b128 v[208:211], v165 offset:17408
	ds_read_b128 v[212:215], v165 offset:18432
	ds_read_b128 v[216:219], v165 offset:19456
	ds_read_b128 v[220:223], v165 offset:20480
	ds_read_b128 v[224:227], v165 offset:21504
	ds_read_b128 v[228:231], v165 offset:22528
	ds_read_b128 v[232:235], v165 offset:23552
	v_lshl_add_u64 v[136:137], s[76:77], 0, v[0:1]
	s_add_i32 m0, s94, 0x8000
	v_lshl_add_u64 v[144:145], s[76:77], 0, v[130:131]
	global_load_lds_dwordx4 v[136:137], off
	s_add_i32 m0, s94, 0xa000
	s_nop 0
	global_load_lds_dwordx4 v[144:145], off
	v_lshl_add_u64 v[182:183], vcc, 0, v[0:1]
	s_add_i32 m0, s93, 0x1c000
	v_lshl_add_u64 v[236:237], vcc, 0, v[130:131]
	global_load_lds_dwordx4 v[182:183], off
	s_add_i32 m0, s93, 0x1e000
	s_nop 0
	global_load_lds_dwordx4 v[236:237], off
	s_cmp_lt_u32 s82, s59
	s_cselect_b32 s83, 0x80, 0
	s_add_u32 s76, s76, s83
	s_addc_u32 s77, s77, 0
	s_add_u32 vcc_lo, vcc_lo, s83
	s_addc_u32 vcc_hi, vcc_hi, 0
	s_add_i32 s82, s82, 1
	s_waitcnt vmcnt(8)
	s_waitcnt lgkmcnt(0)
	s_barrier
; #define PG8_STAGE(bufoff, gbase, voff) do { _Pragma("unroll") for (int _i = 0; _i < 2; ++_i) \
;         __builtin_amdgcn_global_load_lds((const unsigned*)((const char*)(gbase) + (voff)[_i]), (PG8_LAS unsigned*)(lds + (bufoff) + ldsw + _i * 8192), 16, 0, 0); } while (0)
; #define PG8_LDA(dst, b, h) do { _Pragma("unroll") for (int m = 0; m < 4; ++m) _Pragma("unroll") for (int k = 0; k < 2; ++k) dst[m][k] = *(const PG8_LAS bf16x8*)(lds + PG8_SA(b, h) + aoff + m * 2048 + k * 1024); } while (0)
; #define PG8_LDB(dst, b, h) do { _Pragma("unroll") for (int n = 0; n < 2; ++n) _Pragma("unroll") for (int k = 0; k < 2; ++k) dst[n][k] = *(const PG8_LAS bf16x8*)(lds + PG8_SB(b, h) + boff + n * 2048 + k * 1024); } while (0)
; template <class Epi, class Sched, bool ALIGN_EPI = false, bool SP2 = false>
; __device__ __forceinline__ void gemm_phase(PG8_LAS unsigned char* lds, const Gemm g, const Sched& S, const Epi& E) {
;     ...
;         for (int t = 0; t < nt; t += 2) {
;             const bool last = (t == nt - 2);
;             const char* a1 = cA + (size_t)(t + 1) * kstep;
;             const char* a2 = last ? nA : cA + (size_t)(t + 2) * kstep; const char* b2 = last ? nB : cB + (size_t)(t + 2) * kstep;
;             const char* a3 = a2 + kstep; const char* b3 = b2 + kstep;
;             if (last && has_next) S.a_ready(nxt);
;             if constexpr (SP2) {
;             PG8_LDB(B0, 0, 0); PG8_LDB(B1, 0, 1); PG8_SCHED; PG8_LDA(At, 0, 0); PG8_STAGE(PG8_SA(1, 1), a1 + hstep, voffA);
;             PG8_WAIT_V(8); PG8_WAIT_L(0); PG8_BAR; PG8_MMA(0, 0, At, B0); PG8_MMA(0, 1, At, B1); PG8_BAR; PG8_SCHED;
;             PG8_LDA(At, 0, 1); PG8_STAGE(PG8_SB(0, 0), b2, voffB); PG8_STAGE(PG8_SB(0, 1), b2 + hstep, voffB); PG8_STAGE(PG8_SA(0, 0), a2, voffA);
;             PG8_WAIT_V(8); PG8_WAIT_L(0); PG8_BAR; PG8_MMA(1, 0, At, B0); PG8_MMA(1, 1, At, B1); PG8_BAR; PG8_SCHED;
;             PG8_LDB(B0, 1, 0); PG8_LDB(B1, 1, 1); PG8_SCHED; PG8_LDA(At, 1, 0); PG8_STAGE(PG8_SA(0, 1), a2 + hstep, voffA);
;             PG8_WAIT_V(8); PG8_WAIT_L(0); PG8_BAR; PG8_MMA(0, 0, At, B0); PG8_MMA(0, 1, At, B1); PG8_BAR; PG8_SCHED;
;             PG8_LDA(At, 1, 1); PG8_STAGE(PG8_SB(1, 0), b3, voffB); PG8_STAGE(PG8_SB(1, 1), b3 + hstep, voffB); PG8_STAGE(PG8_SA(1, 0), a3, voffA);
;             PG8_WAIT_V(8); PG8_WAIT_L(0); PG8_BAR; PG8_MMA(1, 0, At, B0); PG8_MMA(1, 1, At, B1); PG8_BAR; PG8_SCHED;
	s_setprio 1
	v_mfma_f32_16x16x32_bf16 v[118:121], v[166:169], v[202:205], v[118:121]
	v_mfma_f32_16x16x32_bf16 v[114:117], v[174:177], v[202:205], v[114:117]
	v_mfma_f32_16x16x32_bf16 v[102:105], v[166:169], v[212:215], v[102:105]
	v_mfma_f32_16x16x32_bf16 v[98:101], v[174:177], v[212:215], v[98:101]
	v_mfma_f32_16x16x32_bf16 v[86:89], v[166:169], v[220:223], v[86:89]
	v_mfma_f32_16x16x32_bf16 v[82:85], v[174:177], v[220:223], v[82:85]
	v_mfma_f32_16x16x32_bf16 v[70:73], v[166:169], v[228:231], v[70:73]
	v_mfma_f32_16x16x32_bf16 v[66:69], v[174:177], v[228:231], v[66:69]
	v_mfma_f32_16x16x32_bf16 v[118:121], v[170:173], v[208:211], v[118:121]
	v_mfma_f32_16x16x32_bf16 v[114:117], v[178:181], v[208:211], v[114:117]
	v_mfma_f32_16x16x32_bf16 v[102:105], v[170:173], v[216:219], v[102:105]
	v_mfma_f32_16x16x32_bf16 v[98:101], v[178:181], v[216:219], v[98:101]
	v_mfma_f32_16x16x32_bf16 v[86:89], v[170:173], v[224:227], v[86:89]
	v_mfma_f32_16x16x32_bf16 v[82:85], v[178:181], v[224:227], v[82:85]
	v_mfma_f32_16x16x32_bf16 v[70:73], v[170:173], v[232:235], v[70:73]
	v_mfma_f32_16x16x32_bf16 v[66:69], v[178:181], v[232:235], v[66:69]
	s_setprio 0
	s_barrier
	v_add_u32_e32 v136, 0x18000, v147
	ds_read_b128 v[166:169], v136
	ds_read_b128 v[170:173], v136 offset:1024
	ds_read_b128 v[174:177], v136 offset:2048
	ds_read_b128 v[178:181], v136 offset:3072
	ds_read_b128 v[202:205], v165 offset:49152
	ds_read_b128 v[208:211], v165 offset:50176
	ds_read_b128 v[212:215], v165 offset:51200
	ds_read_b128 v[216:219], v165 offset:52224
	ds_read_b128 v[220:223], v165 offset:53248
	ds_read_b128 v[224:227], v165 offset:54272
	ds_read_b128 v[228:231], v165 offset:55296
	ds_read_b128 v[232:235], v165 offset:56320
	v_lshl_add_u64 v[136:137], s[76:77], 0, v[0:1]
	s_add_i32 m0, s94, 0x4000
	v_lshl_add_u64 v[144:145], s[76:77], 0, v[130:131]
	global_load_lds_dwordx4 v[136:137], off
	s_add_i32 m0, s94, 0x6000
	s_nop 0
	global_load_lds_dwordx4 v[144:145], off
	v_lshl_add_u64 v[182:183], vcc, 0, v[0:1]
	s_add_i32 m0, s93, 0x10000
	v_lshl_add_u64 v[236:237], vcc, 0, v[130:131]
	global_load_lds_dwordx4 v[182:183], off
	s_add_i32 m0, s93, 0x12000
	s_nop 0
	global_load_lds_dwordx4 v[236:237], off
	s_cmp_lt_u32 s82, s59
	s_cselect_b32 s83, 0x80, 0
	s_add_u32 s76, s76, s83
	s_addc_u32 s77, s77, 0
	s_add_u32 vcc_lo, vcc_lo, s83
	s_addc_u32 vcc_hi, vcc_hi, 0
	s_add_i32 s82, s82, 1
	s_waitcnt vmcnt(8)
	s_waitcnt lgkmcnt(0)
	s_barrier
	s_setprio 1
	v_mfma_f32_16x16x32_bf16 v[118:121], v[166:169], v[202:205], v[118:121]
	v_mfma_f32_16x16x32_bf16 v[114:117], v[174:177], v[202:205], v[114:117]
	v_mfma_f32_16x16x32_bf16 v[102:105], v[166:169], v[212:215], v[102:105]
	v_mfma_f32_16x16x32_bf16 v[98:101], v[174:177], v[212:215], v[98:101]
	v_mfma_f32_16x16x32_bf16 v[86:89], v[166:169], v[220:223], v[86:89]
	v_mfma_f32_16x16x32_bf16 v[82:85], v[174:177], v[220:223], v[82:85]
	v_mfma_f32_16x16x32_bf16 v[70:73], v[166:169], v[228:231], v[70:73]
	v_mfma_f32_16x16x32_bf16 v[66:69], v[174:177], v[228:231], v[66:69]
	v_mfma_f32_16x16x32_bf16 v[118:121], v[170:173], v[208:211], v[118:121]
	v_mfma_f32_16x16x32_bf16 v[114:117], v[178:181], v[208:211], v[114:117]
	v_mfma_f32_16x16x32_bf16 v[102:105], v[170:173], v[216:219], v[102:105]
	v_mfma_f32_16x16x32_bf16 v[98:101], v[178:181], v[216:219], v[98:101]
	v_mfma_f32_16x16x32_bf16 v[86:89], v[170:173], v[224:227], v[86:89]
	v_mfma_f32_16x16x32_bf16 v[82:85], v[178:181], v[224:227], v[82:85]
	v_mfma_f32_16x16x32_bf16 v[70:73], v[170:173], v[232:235], v[70:73]
	v_mfma_f32_16x16x32_bf16 v[66:69], v[178:181], v[232:235], v[66:69]
	s_setprio 0
	s_barrier
	s_add_i32 s83, s82, -3
	s_cmp_lt_u32 s83, s79
	s_cbranch_scc1 .Lkq_3_loop
	s_branch .Lkq_exit
.Lkq_4:
	s_waitcnt vmcnt(0)
	s_barrier
	s_mov_b64 s[76:77], s[48:49]
	s_add_u32 vcc_lo, s80, 0xffffff80
	s_addc_u32 vcc_hi, s81, -1
	s_add_u32 s76, s76, s10
	s_addc_u32 s77, s77, 0
	s_add_u32 vcc_lo, vcc_lo, s10
	s_addc_u32 vcc_hi, vcc_hi, 0
	v_lshl_add_u64 v[136:137], s[76:77], 0, v[0:1]
	s_add_i32 m0, s94, 0xc000
	v_lshl_add_u64 v[144:145], s[76:77], 0, v[130:131]
	global_load_lds_dwordx4 v[136:137], off
	s_add_i32 m0, s94, 0xe000
	s_nop 0
	global_load_lds_dwordx4 v[144:145], off
	s_add_u32 s76, s76, 0x80
	s_addc_u32 s77, s77, 0
	s_add_u32 vcc_lo, vcc_lo, 0x80
	s_addc_u32 vcc_hi, vcc_hi, 0
	v_lshl_add_u64 v[136:137], s[76:77], 0, v[0:1]
	s_add_i32 m0, s94, 0x0
	v_lshl_add_u64 v[144:145], s[76:77], 0, v[130:131]
	global_load_lds_dwordx4 v[136:137], off
	s_add_i32 m0, s94, 0x2000
	s_nop 0
	global_load_lds_dwordx4 v[144:145], off
	v_lshl_add_u64 v[182:183], vcc, 0, v[0:1]
	s_add_i32 m0, s93, 0x10000
	v_lshl_add_u64 v[236:237], vcc, 0, v[130:131]
	global_load_lds_dwordx4 v[182:183], off
	s_add_i32 m0, s93, 0x12000
	s_nop 0
	global_load_lds_dwordx4 v[236:237], off
	s_add_u32 s76, s76, 0x80
	s_addc_u32 s77, s77, 0
	s_add_u32 vcc_lo, vcc_lo, 0x80
	s_addc_u32 vcc_hi, vcc_hi, 0
	s_mov_b32 s82, 3
	s_add_i32 s59, s79, -1
; #define PG8_STAGE(bufoff, gbase, voff) do { _Pragma("unroll") for (int _i = 0; _i < 2; ++_i) \
;         __builtin_amdgcn_global_load_lds((const unsigned*)((const char*)(gbase) + (voff)[_i]), (PG8_LAS unsigned*)(lds + (bufoff) + ldsw + _i * 8192), 16, 0, 0); } while (0)
; #define PG8_LDA(dst, b, h) do { _Pragma("unroll") for (int m = 0; m < 4; ++m) _Pragma("unroll") for (int k = 0; k < 2; ++k) dst[m][k] = *(const PG8_LAS bf16x8*)(lds + PG8_SA(b, h) + aoff + m * 2048 + k * 1024); } while (0)
; #define PG8_LDB(dst, b, h) do { _Pragma("unroll") for (int n = 0; n < 2; ++n) _Pragma("unroll") for (int k = 0; k < 2; ++k) dst[n][k] = *(const PG8_LAS bf16x8*)(lds + PG8_SB(b, h) + boff + n * 2048 + k * 1024); } while (0)
; template <class Epi, class Sched, bool ALIGN_EPI = false, bool SP2 = false>
; __device__ __forceinline__ void gemm_phase(PG8_LAS unsigned char* lds, const Gemm g, const Sched& S, const Epi& E) {
;     ...
;         for (int t = 0; t < nt; t += 2) {
;             const bool last = (t == nt - 2);
;             const char* a1 = cA + (size_t)(t + 1) * kstep;
;             const char* a2 = last ? nA : cA + (size_t)(t + 2) * kstep; const char* b2 = last ? nB : cB + (size_t)(t + 2) * kstep;
;             const char* a3 = a2 + kstep; const char* b3 = b2 + kstep;
;             if (last && has_next) S.a_ready(nxt);
;             if constexpr (SP2) {
;             PG8_LDB(B0, 0, 0); PG8_LDB(B1, 0, 1); PG8_SCHED; PG8_LDA(At, 0, 0); PG8_STAGE(PG8_SA(1, 1), a1 + hstep, voffA);
;             PG8_WAIT_V(8); PG8_WAIT_L(0); PG8_BAR; PG8_MMA(0, 0, At, B0); PG8_MMA(0, 1, At, B1); PG8_BAR; PG8_SCHED;
;             PG8_LDA(At, 0, 1); PG8_STAGE(PG8_SB(0, 0), b2, voffB); PG8_STAGE(PG8_SB(0, 1), b2 + hstep, voffB); PG8_STAGE(PG8_SA(0, 0), a2, voffA);
;             PG8_WAIT_V(8); PG8_WAIT_L(0); PG8_BAR; PG8_MMA(1, 0, At, B0); PG8_MMA(1, 1, At, B1); PG8_BAR; PG8_SCHED;
;             PG8_LDB(B0, 1, 0); PG8_LDB(B1, 1, 1); PG8_SCHED; PG8_LDA(At, 1, 0); PG8_STAGE(PG8_SA(0, 1), a2 + hstep, voffA);
;             PG8_WAIT_V(8); PG8_WAIT_L(0); PG8_BAR; PG8_MMA(0, 0, At, B0); PG8_MMA(0, 1, At, B1); PG8_BAR; PG8_SCHED;
;             PG8_LDA(At, 1, 1); PG8_STAGE(PG8_SB(1, 0), b3, voffB); PG8_STAGE(PG8_SB(1, 1), b3 + hstep, voffB); PG8_STAGE(PG8_SA(1, 0), a3, voffA);
;             PG8_WAIT_V(8); PG8_WAIT_L(0); PG8_BAR; PG8_MMA(1, 0, At, B0); PG8_MMA(1, 1, At, B1); PG8_BAR; PG8_SCHED;
.Lkq_4_loop:
	v_add_u32_e32 v136, 0x14000, v147
	ds_read_b128 v[166:169], v136
	ds_read_b128 v[170:173], v136 offset:1024
	ds_read_b128 v[174:177], v136 offset:2048
	ds_read_b128 v[178:181], v136 offset:3072
	ds_read_b128 v[202:205], v165 offset:16384
	ds_read_b128 v[208:211], v165 offset:17408
	ds_read_b128 v[212:215], v165 offset:18432
	ds_read_b128 v[216:219], v165 offset:19456
	ds_read_b128 v[220:223], v165 offset:20480
	ds_read_b128 v[224:227], v165 offset:21504
	ds_read_b128 v[228:231], v165 offset:22528
	ds_read_b128 v[232:235], v165 offset:23552
	v_lshl_add_u64 v[136:137], s[76:77], 0, v[0:1]
	s_add_i32 m0, s94, 0x8000
	v_lshl_add_u64 v[144:145], s[76:77], 0, v[130:131]
	global_load_lds_dwordx4 v[136:137], off
	s_add_i32 m0, s94, 0xa000
	s_nop 0
	global_load_lds_dwordx4 v[144:145], off
	v_lshl_add_u64 v[182:183], vcc, 0, v[0:1]
	s_add_i32 m0, s93, 0x18000
	v_lshl_add_u64 v[236:237], vcc, 0, v[130:131]
	global_load_lds_dwordx4 v[182:183], off
	s_add_i32 m0, s93, 0x1a000
	s_nop 0
	global_load_lds_dwordx4 v[236:237], off
	s_cmp_lt_u32 s82, s59
	s_cselect_b32 s83, 0x80, 0
	s_add_u32 s76, s76, s83
	s_addc_u32 s77, s77, 0
	s_add_u32 vcc_lo, vcc_lo, s83
	s_addc_u32 vcc_hi, vcc_hi, 0
	s_add_i32 s82, s82, 1
	s_waitcnt vmcnt(8)
	s_waitcnt lgkmcnt(0)
	s_barrier
	s_setprio 1
	v_mfma_f32_16x16x32_bf16 v[54:57], v[166:169], v[202:205], v[54:57]
	v_mfma_f32_16x16x32_bf16 v[50:53], v[174:177], v[202:205], v[50:53]
	v_mfma_f32_16x16x32_bf16 v[38:41], v[166:169], v[212:215], v[38:41]
	v_mfma_f32_16x16x32_bf16 v[34:37], v[174:177], v[212:215], v[34:37]
	v_mfma_f32_16x16x32_bf16 v[22:25], v[166:169], v[220:223], v[22:25]
	v_mfma_f32_16x16x32_bf16 v[18:21], v[174:177], v[220:223], v[18:21]
	v_mfma_f32_16x16x32_bf16 v[6:9], v[166:169], v[228:231], v[6:9]
	v_mfma_f32_16x16x32_bf16 v[2:5], v[174:177], v[228:231], v[2:5]
	v_mfma_f32_16x16x32_bf16 v[54:57], v[170:173], v[208:211], v[54:57]
	v_mfma_f32_16x16x32_bf16 v[50:53], v[178:181], v[208:211], v[50:53]
	v_mfma_f32_16x16x32_bf16 v[38:41], v[170:173], v[216:219], v[38:41]
	v_mfma_f32_16x16x32_bf16 v[34:37], v[178:181], v[216:219], v[34:37]
	v_mfma_f32_16x16x32_bf16 v[22:25], v[170:173], v[224:227], v[22:25]
	v_mfma_f32_16x16x32_bf16 v[18:21], v[178:181], v[224:227], v[18:21]
	v_mfma_f32_16x16x32_bf16 v[6:9], v[170:173], v[232:235], v[6:9]
	v_mfma_f32_16x16x32_bf16 v[2:5], v[178:181], v[232:235], v[2:5]
	s_setprio 0
	s_barrier
	v_add_u32_e32 v136, 0x1c000, v147
	ds_read_b128 v[166:169], v136
	ds_read_b128 v[170:173], v136 offset:1024
	ds_read_b128 v[174:177], v136 offset:2048
	ds_read_b128 v[178:181], v136 offset:3072
	ds_read_b128 v[202:205], v165 offset:49152
	ds_read_b128 v[208:211], v165 offset:50176
	ds_read_b128 v[212:215], v165 offset:51200
	ds_read_b128 v[216:219], v165 offset:52224
	ds_read_b128 v[220:223], v165 offset:53248
	ds_read_b128 v[224:227], v165 offset:54272
	ds_read_b128 v[228:231], v165 offset:55296
	ds_read_b128 v[232:235], v165 offset:56320
	v_lshl_add_u64 v[136:137], s[76:77], 0, v[0:1]
	s_add_i32 m0, s94, 0x4000
	v_lshl_add_u64 v[144:145], s[76:77], 0, v[130:131]
	global_load_lds_dwordx4 v[136:137], off
	s_add_i32 m0, s94, 0x6000
	s_nop 0
	global_load_lds_dwordx4 v[144:145], off
	v_lshl_add_u64 v[182:183], vcc, 0, v[0:1]
	s_add_i32 m0, s93, 0x14000
	v_lshl_add_u64 v[236:237], vcc, 0, v[130:131]
	global_load_lds_dwordx4 v[182:183], off
	s_add_i32 m0, s93, 0x16000
	s_nop 0
	global_load_lds_dwordx4 v[236:237], off
	s_cmp_lt_u32 s82, s59
	s_cselect_b32 s83, 0x80, 0
	s_add_u32 s76, s76, s83
	s_addc_u32 s77, s77, 0
	s_add_u32 vcc_lo, vcc_lo, s83
	s_addc_u32 vcc_hi, vcc_hi, 0
	s_add_i32 s82, s82, 1
	s_waitcnt vmcnt(8)
	s_waitcnt lgkmcnt(0)
	s_barrier
	s_setprio 1
	v_mfma_f32_16x16x32_bf16 v[54:57], v[166:169], v[202:205], v[54:57]
	v_mfma_f32_16x16x32_bf16 v[50:53], v[174:177], v[202:205], v[50:53]
	v_mfma_f32_16x16x32_bf16 v[38:41], v[166:169], v[212:215], v[38:41]
	v_mfma_f32_16x16x32_bf16 v[34:37], v[174:177], v[212:215], v[34:37]
	v_mfma_f32_16x16x32_bf16 v[22:25], v[166:169], v[220:223], v[22:25]
	v_mfma_f32_16x16x32_bf16 v[18:21], v[174:177], v[220:223], v[18:21]
	v_mfma_f32_16x16x32_bf16 v[6:9], v[166:169], v[228:231], v[6:9]
	v_mfma_f32_16x16x32_bf16 v[2:5], v[174:177], v[228:231], v[2:5]
	v_mfma_f32_16x16x32_bf16 v[54:57], v[170:173], v[208:211], v[54:57]
	v_mfma_f32_16x16x32_bf16 v[50:53], v[178:181], v[208:211], v[50:53]
	v_mfma_f32_16x16x32_bf16 v[38:41], v[170:173], v[216:219], v[38:41]
	v_mfma_f32_16x16x32_bf16 v[34:37], v[178:181], v[216:219], v[34:37]
	v_mfma_f32_16x16x32_bf16 v[22:25], v[170:173], v[224:227], v[22:25]
	v_mfma_f32_16x16x32_bf16 v[18:21], v[178:181], v[224:227], v[18:21]
	v_mfma_f32_16x16x32_bf16 v[6:9], v[170:173], v[232:235], v[6:9]
	v_mfma_f32_16x16x32_bf16 v[2:5], v[178:181], v[232:235], v[2:5]
	s_setprio 0
	s_barrier
; #define PG8_STAGE(bufoff, gbase, voff) do { _Pragma("unroll") for (int _i = 0; _i < 2; ++_i) \
;         __builtin_amdgcn_global_load_lds((const unsigned*)((const char*)(gbase) + (voff)[_i]), (PG8_LAS unsigned*)(lds + (bufoff) + ldsw + _i * 8192), 16, 0, 0); } while (0)
; #define PG8_LDA(dst, b, h) do { _Pragma("unroll") for (int m = 0; m < 4; ++m) _Pragma("unroll") for (int k = 0; k < 2; ++k) dst[m][k] = *(const PG8_LAS bf16x8*)(lds + PG8_SA(b, h) + aoff + m * 2048 + k * 1024); } while (0)
; #define PG8_LDB(dst, b, h) do { _Pragma("unroll") for (int n = 0; n < 2; ++n) _Pragma("unroll") for (int k = 0; k < 2; ++k) dst[n][k] = *(const PG8_LAS bf16x8*)(lds + PG8_SB(b, h) + boff + n * 2048 + k * 1024); } while (0)
; template <class Epi, class Sched, bool ALIGN_EPI = false, bool SP2 = false>
; __device__ __forceinline__ void gemm_phase(PG8_LAS unsigned char* lds, const Gemm g, const Sched& S, const Epi& E) {
;     ...
;         for (int t = 0; t < nt; t += 2) {
;             const bool last = (t == nt - 2);
;             const char* a1 = cA + (size_t)(t + 1) * kstep;
;             const char* a2 = last ? nA : cA + (size_t)(t + 2) * kstep; const char* b2 = last ? nB : cB + (size_t)(t + 2) * kstep;
;             const char* a3 = a2 + kstep; const char* b3 = b2 + kstep;
;             if (last && has_next) S.a_ready(nxt);
;             if constexpr (SP2) {
;             PG8_LDB(B0, 0, 0); PG8_LDB(B1, 0, 1); PG8_SCHED; PG8_LDA(At, 0, 0); PG8_STAGE(PG8_SA(1, 1), a1 + hstep, voffA);
;             PG8_WAIT_V(8); PG8_WAIT_L(0); PG8_BAR; PG8_MMA(0, 0, At, B0); PG8_MMA(0, 1, At, B1); PG8_BAR; PG8_SCHED;
;             PG8_LDA(At, 0, 1); PG8_STAGE(PG8_SB(0, 0), b2, voffB); PG8_STAGE(PG8_SB(0, 1), b2 + hstep, voffB); PG8_STAGE(PG8_SA(0, 0), a2, voffA);
;             PG8_WAIT_V(8); PG8_WAIT_L(0); PG8_BAR; PG8_MMA(1, 0, At, B0); PG8_MMA(1, 1, At, B1); PG8_BAR; PG8_SCHED;
;             PG8_LDB(B0, 1, 0); PG8_LDB(B1, 1, 1); PG8_SCHED; PG8_LDA(At, 1, 0); PG8_STAGE(PG8_SA(0, 1), a2 + hstep, voffA);
;             PG8_WAIT_V(8); PG8_WAIT_L(0); PG8_BAR; PG8_MMA(0, 0, At, B0); PG8_MMA(0, 1, At, B1); PG8_BAR; PG8_SCHED;
;             PG8_LDA(At, 1, 1); PG8_STAGE(PG8_SB(1, 0), b3, voffB); PG8_STAGE(PG8_SB(1, 1), b3 + hstep, voffB); PG8_STAGE(PG8_SA(1, 0), a3, voffA);
;             PG8_WAIT_V(8); PG8_WAIT_L(0); PG8_BAR; PG8_MMA(1, 0, At, B0); PG8_MMA(1, 1, At, B1); PG8_BAR; PG8_SCHED;
	v_add_u32_e32 v136, 0x10000, v147
	ds_read_b128 v[166:169], v136
	ds_read_b128 v[170:173], v136 offset:1024
	ds_read_b128 v[174:177], v136 offset:2048
	ds_read_b128 v[178:181], v136 offset:3072
	ds_read_b128 v[202:205], v165
	ds_read_b128 v[208:211], v165 offset:1024
	ds_read_b128 v[212:215], v165 offset:2048
	ds_read_b128 v[216:219], v165 offset:3072
	ds_read_b128 v[220:223], v165 offset:4096
	ds_read_b128 v[224:227], v165 offset:5120
	ds_read_b128 v[228:231], v165 offset:6144
	ds_read_b128 v[232:235], v165 offset:7168
	v_lshl_add_u64 v[136:137], s[76:77], 0, v[0:1]
	s_add_i32 m0, s94, 0xc000
	v_lshl_add_u64 v[144:145], s[76:77], 0, v[130:131]
	global_load_lds_dwordx4 v[136:137], off
	s_add_i32 m0, s94, 0xe000
	s_nop 0
	global_load_lds_dwordx4 v[144:145], off
	v_lshl_add_u64 v[182:183], vcc, 0, v[0:1]
	s_add_i32 m0, s93, 0x1c000
	v_lshl_add_u64 v[236:237], vcc, 0, v[130:131]
	global_load_lds_dwordx4 v[182:183], off
	s_add_i32 m0, s93, 0x1e000
	s_nop 0
	global_load_lds_dwordx4 v[236:237], off
	s_cmp_lt_u32 s82, s59
	s_cselect_b32 s83, 0x80, 0
	s_add_u32 s76, s76, s83
	s_addc_u32 s77, s77, 0
	s_add_u32 vcc_lo, vcc_lo, s83
	s_addc_u32 vcc_hi, vcc_hi, 0
	s_add_i32 s82, s82, 1
	s_waitcnt vmcnt(8)
	s_waitcnt lgkmcnt(0)
	s_barrier
	s_setprio 1
	v_mfma_f32_16x16x32_bf16 v[54:57], v[166:169], v[202:205], v[54:57]
	v_mfma_f32_16x16x32_bf16 v[50:53], v[174:177], v[202:205], v[50:53]
	v_mfma_f32_16x16x32_bf16 v[38:41], v[166:169], v[212:215], v[38:41]
	v_mfma_f32_16x16x32_bf16 v[34:37], v[174:177], v[212:215], v[34:37]
	v_mfma_f32_16x16x32_bf16 v[22:25], v[166:169], v[220:223], v[22:25]
	v_mfma_f32_16x16x32_bf16 v[18:21], v[174:177], v[220:223], v[18:21]
	v_mfma_f32_16x16x32_bf16 v[6:9], v[166:169], v[228:231], v[6:9]
	v_mfma_f32_16x16x32_bf16 v[2:5], v[174:177], v[228:231], v[2:5]
	v_mfma_f32_16x16x32_bf16 v[54:57], v[170:173], v[208:211], v[54:57]
	v_mfma_f32_16x16x32_bf16 v[50:53], v[178:181], v[208:211], v[50:53]
	v_mfma_f32_16x16x32_bf16 v[38:41], v[170:173], v[216:219], v[38:41]
	v_mfma_f32_16x16x32_bf16 v[34:37], v[178:181], v[216:219], v[34:37]
	v_mfma_f32_16x16x32_bf16 v[22:25], v[170:173], v[224:227], v[22:25]
	v_mfma_f32_16x16x32_bf16 v[18:21], v[178:181], v[224:227], v[18:21]
	v_mfma_f32_16x16x32_bf16 v[6:9], v[170:173], v[232:235], v[6:9]
	v_mfma_f32_16x16x32_bf16 v[2:5], v[178:181], v[232:235], v[2:5]
	s_setprio 0
	s_barrier
	v_add_u32_e32 v136, 0x18000, v147
	ds_read_b128 v[166:169], v136
	ds_read_b128 v[170:173], v136 offset:1024
	ds_read_b128 v[174:177], v136 offset:2048
	ds_read_b128 v[178:181], v136 offset:3072
	ds_read_b128 v[202:205], v165 offset:32768
	ds_read_b128 v[208:211], v165 offset:33792
	ds_read_b128 v[212:215], v165 offset:34816
	ds_read_b128 v[216:219], v165 offset:35840
	ds_read_b128 v[220:223], v165 offset:36864
	ds_read_b128 v[224:227], v165 offset:37888
	ds_read_b128 v[228:231], v165 offset:38912
	ds_read_b128 v[232:235], v165 offset:39936
	v_lshl_add_u64 v[136:137], s[76:77], 0, v[0:1]
	s_add_i32 m0, s94, 0x0
	v_lshl_add_u64 v[144:145], s[76:77], 0, v[130:131]
	global_load_lds_dwordx4 v[136:137], off
	s_add_i32 m0, s94, 0x2000
	s_nop 0
	global_load_lds_dwordx4 v[144:145], off
	v_lshl_add_u64 v[182:183], vcc, 0, v[0:1]
	s_add_i32 m0, s93, 0x10000
	v_lshl_add_u64 v[236:237], vcc, 0, v[130:131]
	global_load_lds_dwordx4 v[182:183], off
	s_add_i32 m0, s93, 0x12000
	s_nop 0
	global_load_lds_dwordx4 v[236:237], off
	s_cmp_lt_u32 s82, s59
	s_cselect_b32 s83, 0x80, 0
	s_add_u32 s76, s76, s83
	s_addc_u32 s77, s77, 0
	s_add_u32 vcc_lo, vcc_lo, s83
	s_addc_u32 vcc_hi, vcc_hi, 0
	s_add_i32 s82, s82, 1
	s_waitcnt vmcnt(8)
	s_waitcnt lgkmcnt(0)
	s_barrier
	s_setprio 1
	v_mfma_f32_16x16x32_bf16 v[54:57], v[166:169], v[202:205], v[54:57]
	v_mfma_f32_16x16x32_bf16 v[50:53], v[174:177], v[202:205], v[50:53]
	v_mfma_f32_16x16x32_bf16 v[38:41], v[166:169], v[212:215], v[38:41]
	v_mfma_f32_16x16x32_bf16 v[34:37], v[174:177], v[212:215], v[34:37]
	v_mfma_f32_16x16x32_bf16 v[22:25], v[166:169], v[220:223], v[22:25]
	v_mfma_f32_16x16x32_bf16 v[18:21], v[174:177], v[220:223], v[18:21]
	v_mfma_f32_16x16x32_bf16 v[6:9], v[166:169], v[228:231], v[6:9]
	v_mfma_f32_16x16x32_bf16 v[2:5], v[174:177], v[228:231], v[2:5]
	v_mfma_f32_16x16x32_bf16 v[54:57], v[170:173], v[208:211], v[54:57]
	v_mfma_f32_16x16x32_bf16 v[50:53], v[178:181], v[208:211], v[50:53]
	v_mfma_f32_16x16x32_bf16 v[38:41], v[170:173], v[216:219], v[38:41]
	v_mfma_f32_16x16x32_bf16 v[34:37], v[178:181], v[216:219], v[34:37]
	v_mfma_f32_16x16x32_bf16 v[22:25], v[170:173], v[224:227], v[22:25]
	v_mfma_f32_16x16x32_bf16 v[18:21], v[178:181], v[224:227], v[18:21]
	v_mfma_f32_16x16x32_bf16 v[6:9], v[170:173], v[232:235], v[6:9]
	v_mfma_f32_16x16x32_bf16 v[2:5], v[178:181], v[232:235], v[2:5]
	s_setprio 0
	s_barrier
	s_add_i32 s83, s82, -3
	s_cmp_lt_u32 s83, s79
	s_cbranch_scc1 .Lkq_4_loop
